# EpiResid (W_o, FFN down): the eight exec-masked per-row partial-sum stores merged into four stores at the epilogue end
# speedup vs baseline: 1.0024x; 1.0024x over previous
.LBB0_1022:
	s_lshl_b32 s0, s79, 8
	v_mov_b32_e32 v140, v193
	s_add_i32 s0, s0, s55
	v_mul_f32_e32 v148, v115, v115
	v_bfe_u32 v143, v140, 4, 2
	v_and_or_b32 v142, v140, 15, s0
	s_lshl_b32 s0, s4, 8
	v_lshl_or_b32 v140, v143, 3, s0
	v_cmp_eq_u32_e32 vcc, 0, v143
	v_ashrrev_i32_e32 v143, 31, v142
	v_or_b32_e32 v140, s71, v140
	v_lshlrev_b64 v[146:147], 11, v[142:143]
	v_ashrrev_i32_e32 v141, 31, v140
	v_lshl_add_u64 v[146:147], s[2:3], 0, v[146:147]
	v_mul_f32_e32 v149, v117, v117
	v_lshl_add_u64 v[146:147], v[140:141], 1, v[146:147]
	v_fmac_f32_e32 v148, v114, v114
	v_fmac_f32_e32 v149, v116, v116
	v_cvt_pk_bf16_f32 v114, v114, v115
	v_cvt_pk_bf16_f32 v115, v116, v117
	v_cvt_pk_bf16_f32 v116, v118, v119
	v_cvt_pk_bf16_f32 v117, v120, v121
	flat_store_dwordx4 v[146:147], v[114:117]
	v_add_f32_e32 v148, v148, v149
	v_mul_f32_e32 v149, v119, v119
	v_mul_f32_e32 v114, v123, v123
	v_mul_f32_e32 v115, v125, v125
	v_fmac_f32_e32 v114, v122, v122
	v_fmac_f32_e32 v115, v124, v124
	v_mul_f32_e32 v150, v121, v121
	v_add_f32_e32 v114, v114, v115
	v_mul_f32_e32 v115, v127, v127
	v_mul_f32_e32 v116, v129, v129
	v_fmac_f32_e32 v149, v118, v118
	v_fmac_f32_e32 v150, v120, v120
	v_fmac_f32_e32 v115, v126, v126
	v_fmac_f32_e32 v116, v128, v128
	v_add_f32_e32 v149, v149, v150
	v_add_f32_e32 v115, v115, v116
	v_add_f32_e32 v148, v148, v149
	v_add_f32_e32 v114, v114, v115
	v_add_f32_e32 v118, v148, v114
	ds_swizzle_b32 v119, v118 offset:swizzle(SWAP,16)
	v_cvt_pk_bf16_f32 v114, v122, v123
	v_cvt_pk_bf16_f32 v115, v124, v125
	v_cvt_pk_bf16_f32 v116, v126, v127
	v_cvt_pk_bf16_f32 v117, v128, v129
	flat_store_dwordx4 v[146:147], v[114:117] offset:256
	s_lshl_b32 s24, s4, 2
	s_ashr_i32 s25, s24, 31
	s_waitcnt lgkmcnt(0)
	v_add_f32_e32 v114, v118, v119
	v_mov_b32_e32 v115, v114
	s_nop 1
	v_permlane32_swap_b32_e32 v114, v115
	v_add_f32_e32 v151, v114, v115
	v_or_b32_e32 v114, 16, v142
	v_ashrrev_i32_e32 v115, 31, v114
	v_lshlrev_b64 v[116:117], 11, v[114:115]
	v_lshl_add_u64 v[116:117], s[2:3], 0, v[116:117]
	v_mul_f32_e32 v118, v99, v99
	v_mul_f32_e32 v119, v101, v101
	v_lshl_add_u64 v[116:117], v[140:141], 1, v[116:117]
	v_fmac_f32_e32 v118, v98, v98
	v_fmac_f32_e32 v119, v100, v100
	v_cvt_pk_bf16_f32 v98, v98, v99
	v_cvt_pk_bf16_f32 v99, v100, v101
	v_cvt_pk_bf16_f32 v100, v102, v103
	v_cvt_pk_bf16_f32 v101, v104, v105
	flat_store_dwordx4 v[116:117], v[98:101]
	v_add_f32_e32 v118, v118, v119
	v_mul_f32_e32 v119, v103, v103
	v_mul_f32_e32 v98, v107, v107
	v_mul_f32_e32 v99, v109, v109
	v_fmac_f32_e32 v98, v106, v106
	v_fmac_f32_e32 v99, v108, v108
	v_mul_f32_e32 v120, v105, v105
	v_add_f32_e32 v98, v98, v99
	v_mul_f32_e32 v99, v111, v111
	v_mul_f32_e32 v100, v113, v113
	v_fmac_f32_e32 v119, v102, v102
	v_fmac_f32_e32 v120, v104, v104
	v_fmac_f32_e32 v99, v110, v110
	v_fmac_f32_e32 v100, v112, v112
	v_add_f32_e32 v119, v119, v120
	v_add_f32_e32 v99, v99, v100
	v_add_f32_e32 v118, v118, v119
	v_add_f32_e32 v98, v98, v99
	v_add_f32_e32 v102, v118, v98
	ds_swizzle_b32 v103, v102 offset:swizzle(SWAP,16)
	v_cvt_pk_bf16_f32 v98, v106, v107
	v_cvt_pk_bf16_f32 v99, v108, v109
	v_cvt_pk_bf16_f32 v100, v110, v111
	v_cvt_pk_bf16_f32 v101, v112, v113
	flat_store_dwordx4 v[116:117], v[98:101] offset:256
	s_waitcnt lgkmcnt(0)
	s_nop 0
	v_add_f32_e32 v98, v102, v103
	v_mov_b32_e32 v99, v98
	s_nop 1
	v_permlane32_swap_b32_e32 v98, v99
	v_add_f32_e32 v152, v98, v99
	v_or_b32_e32 v98, 32, v142
	v_ashrrev_i32_e32 v99, 31, v98
	v_lshlrev_b64 v[100:101], 11, v[98:99]
	v_lshl_add_u64 v[100:101], s[2:3], 0, v[100:101]
	v_mul_f32_e32 v102, v71, v71
	v_mul_f32_e32 v103, v73, v73
	v_lshl_add_u64 v[100:101], v[140:141], 1, v[100:101]
	v_fmac_f32_e32 v102, v70, v70
	v_fmac_f32_e32 v103, v72, v72
	v_cvt_pk_bf16_f32 v70, v70, v71
	v_cvt_pk_bf16_f32 v71, v72, v73
	v_cvt_pk_bf16_f32 v72, v78, v79
	v_cvt_pk_bf16_f32 v73, v80, v81
	flat_store_dwordx4 v[100:101], v[70:73]
	v_add_f32_e32 v102, v102, v103
	v_mul_f32_e32 v103, v79, v79
	v_mul_f32_e32 v70, v87, v87
	v_mul_f32_e32 v71, v89, v89
	v_fmac_f32_e32 v70, v86, v86
	v_fmac_f32_e32 v71, v88, v88
	v_mul_f32_e32 v104, v81, v81
	v_add_f32_e32 v70, v70, v71
	v_mul_f32_e32 v71, v95, v95
	v_mul_f32_e32 v72, v97, v97
	v_fmac_f32_e32 v103, v78, v78
	v_fmac_f32_e32 v104, v80, v80
	v_fmac_f32_e32 v71, v94, v94
	v_fmac_f32_e32 v72, v96, v96
	v_add_f32_e32 v103, v103, v104
	v_add_f32_e32 v71, v71, v72
	v_add_f32_e32 v102, v102, v103
	v_add_f32_e32 v70, v70, v71
	v_add_f32_e32 v78, v102, v70
	ds_swizzle_b32 v79, v78 offset:swizzle(SWAP,16)
	v_cvt_pk_bf16_f32 v70, v86, v87
	v_cvt_pk_bf16_f32 v71, v88, v89
	v_cvt_pk_bf16_f32 v72, v94, v95
	v_cvt_pk_bf16_f32 v73, v96, v97
	flat_store_dwordx4 v[100:101], v[70:73] offset:256
	s_waitcnt lgkmcnt(0)
	s_nop 0
	v_add_f32_e32 v70, v78, v79
	v_mov_b32_e32 v71, v70
	s_nop 1
	v_permlane32_swap_b32_e32 v70, v71
	v_add_f32_e32 v153, v70, v71
	v_or_b32_e32 v70, 48, v142
	v_ashrrev_i32_e32 v71, 31, v70
	v_lshlrev_b64 v[72:73], 11, v[70:71]
	v_lshl_add_u64 v[72:73], s[2:3], 0, v[72:73]
	v_mul_f32_e32 v78, v35, v35
	v_mul_f32_e32 v79, v37, v37
	v_lshl_add_u64 v[72:73], v[140:141], 1, v[72:73]
	v_fmac_f32_e32 v78, v34, v34
	v_fmac_f32_e32 v79, v36, v36
	v_cvt_pk_bf16_f32 v34, v34, v35
	v_cvt_pk_bf16_f32 v35, v36, v37
	v_cvt_pk_bf16_f32 v36, v46, v47
	v_cvt_pk_bf16_f32 v37, v48, v49
	flat_store_dwordx4 v[72:73], v[34:37]
	v_add_f32_e32 v78, v78, v79
	v_mul_f32_e32 v79, v47, v47
	v_mul_f32_e32 v34, v59, v59
	v_mul_f32_e32 v35, v61, v61
	v_fmac_f32_e32 v34, v58, v58
	v_fmac_f32_e32 v35, v60, v60
	v_mul_f32_e32 v80, v49, v49
	v_add_f32_e32 v34, v34, v35
	v_mul_f32_e32 v35, v67, v67
	v_mul_f32_e32 v36, v69, v69
	v_fmac_f32_e32 v79, v46, v46
	v_fmac_f32_e32 v80, v48, v48
	v_fmac_f32_e32 v35, v66, v66
	v_fmac_f32_e32 v36, v68, v68
	v_add_f32_e32 v79, v79, v80
	v_add_f32_e32 v35, v35, v36
	v_add_f32_e32 v78, v78, v79
	v_add_f32_e32 v34, v34, v35
	v_add_f32_e32 v46, v78, v34
	ds_swizzle_b32 v47, v46 offset:swizzle(SWAP,16)
	v_cvt_pk_bf16_f32 v34, v58, v59
	v_cvt_pk_bf16_f32 v35, v60, v61
	v_cvt_pk_bf16_f32 v36, v66, v67
	v_cvt_pk_bf16_f32 v37, v68, v69
	flat_store_dwordx4 v[72:73], v[34:37] offset:256
	s_waitcnt lgkmcnt(0)
	s_nop 0
	v_add_f32_e32 v34, v46, v47
	v_mov_b32_e32 v35, v34
	s_nop 1
	v_permlane32_swap_b32_e32 v34, v35
	v_add_f32_e32 v154, v34, v35
	v_add_u32_e32 v34, 0x80, v142
	v_ashrrev_i32_e32 v35, 31, v34
	v_lshlrev_b64 v[36:37], 11, v[34:35]
	v_lshl_add_u64 v[36:37], s[2:3], 0, v[36:37]
	v_mul_f32_e32 v46, v23, v23
	v_mul_f32_e32 v47, v25, v25
	v_lshl_add_u64 v[36:37], v[140:141], 1, v[36:37]
	v_fmac_f32_e32 v46, v22, v22
	v_fmac_f32_e32 v47, v24, v24
	v_cvt_pk_bf16_f32 v22, v22, v23
	v_cvt_pk_bf16_f32 v23, v24, v25
	v_cvt_pk_bf16_f32 v24, v30, v31
	v_cvt_pk_bf16_f32 v25, v32, v33
	flat_store_dwordx4 v[36:37], v[22:25]
	v_add_f32_e32 v46, v46, v47
	v_mul_f32_e32 v47, v31, v31
	v_mul_f32_e32 v22, v39, v39
	v_mul_f32_e32 v23, v41, v41
	v_fmac_f32_e32 v22, v38, v38
	v_fmac_f32_e32 v23, v40, v40
	v_mul_f32_e32 v48, v33, v33
	v_add_f32_e32 v22, v22, v23
	v_mul_f32_e32 v23, v55, v55
	v_mul_f32_e32 v24, v57, v57
	v_fmac_f32_e32 v47, v30, v30
	v_fmac_f32_e32 v48, v32, v32
	v_fmac_f32_e32 v23, v54, v54
	v_fmac_f32_e32 v24, v56, v56
	v_add_f32_e32 v47, v47, v48
	v_add_f32_e32 v23, v23, v24
	v_add_f32_e32 v46, v46, v47
	v_add_f32_e32 v22, v22, v23
	v_add_f32_e32 v30, v46, v22
	ds_swizzle_b32 v31, v30 offset:swizzle(SWAP,16)
	v_cvt_pk_bf16_f32 v22, v38, v39
	v_cvt_pk_bf16_f32 v23, v40, v41
	v_cvt_pk_bf16_f32 v24, v54, v55
	v_cvt_pk_bf16_f32 v25, v56, v57
	flat_store_dwordx4 v[36:37], v[22:25] offset:256
	s_waitcnt lgkmcnt(0)
	s_nop 0
	v_add_f32_e32 v22, v30, v31
	v_mov_b32_e32 v23, v22
	s_nop 1
	v_permlane32_swap_b32_e32 v22, v23
	v_add_f32_e32 v155, v22, v23
	v_add_u32_e32 v22, 0x90, v142
	v_ashrrev_i32_e32 v23, 31, v22
	v_lshlrev_b64 v[24:25], 11, v[22:23]
	v_lshl_add_u64 v[24:25], s[2:3], 0, v[24:25]
	v_mul_f32_e32 v30, v3, v3
	v_mul_f32_e32 v31, v5, v5
	v_lshl_add_u64 v[24:25], v[140:141], 1, v[24:25]
	v_fmac_f32_e32 v30, v2, v2
	v_fmac_f32_e32 v31, v4, v4
	v_cvt_pk_bf16_f32 v2, v2, v3
	v_cvt_pk_bf16_f32 v3, v4, v5
	v_cvt_pk_bf16_f32 v4, v74, v75
	v_cvt_pk_bf16_f32 v5, v76, v77
	flat_store_dwordx4 v[24:25], v[2:5]
	v_add_f32_e32 v30, v30, v31
	v_mul_f32_e32 v31, v75, v75
	v_mul_f32_e32 v2, v83, v83
	v_mul_f32_e32 v3, v85, v85
	v_fmac_f32_e32 v2, v82, v82
	v_fmac_f32_e32 v3, v84, v84
	v_mul_f32_e32 v32, v77, v77
	v_add_f32_e32 v2, v2, v3
	v_mul_f32_e32 v3, v91, v91
	v_mul_f32_e32 v4, v93, v93
	v_fmac_f32_e32 v31, v74, v74
	v_fmac_f32_e32 v32, v76, v76
	v_fmac_f32_e32 v3, v90, v90
	v_fmac_f32_e32 v4, v92, v92
	v_add_f32_e32 v31, v31, v32
	v_add_f32_e32 v3, v3, v4
	v_add_f32_e32 v30, v30, v31
	v_add_f32_e32 v2, v2, v3
	v_add_f32_e32 v30, v30, v2
	ds_swizzle_b32 v31, v30 offset:swizzle(SWAP,16)
	v_cvt_pk_bf16_f32 v2, v82, v83
	v_cvt_pk_bf16_f32 v3, v84, v85
	v_cvt_pk_bf16_f32 v4, v90, v91
	v_cvt_pk_bf16_f32 v5, v92, v93
	flat_store_dwordx4 v[24:25], v[2:5] offset:256
	s_waitcnt lgkmcnt(0)
	s_nop 0
	v_add_f32_e32 v2, v30, v31
	v_mov_b32_e32 v3, v2
	s_nop 1
	v_permlane32_swap_b32_e32 v2, v3
	v_add_f32_e32 v156, v2, v3
	v_mul_f32_e32 v22, v27, v27
	v_mul_f32_e32 v23, v29, v29
	v_add_u32_e32 v2, 0xa0, v142
	v_fmac_f32_e32 v22, v26, v26
	v_fmac_f32_e32 v23, v28, v28
	v_ashrrev_i32_e32 v3, 31, v2
	v_add_f32_e32 v22, v22, v23
	v_mul_f32_e32 v23, v43, v43
	v_mul_f32_e32 v24, v45, v45
	v_lshlrev_b64 v[4:5], 11, v[2:3]
	v_fmac_f32_e32 v23, v42, v42
	v_fmac_f32_e32 v24, v44, v44
	v_lshl_add_u64 v[4:5], s[2:3], 0, v[4:5]
	v_add_f32_e32 v23, v23, v24
	v_lshl_add_u64 v[4:5], v[140:141], 1, v[4:5]
	v_add_f32_e32 v30, v22, v23
	v_cvt_pk_bf16_f32 v22, v26, v27
	v_cvt_pk_bf16_f32 v23, v28, v29
	v_cvt_pk_bf16_f32 v24, v42, v43
	v_cvt_pk_bf16_f32 v25, v44, v45
	flat_store_dwordx4 v[4:5], v[22:25]
	s_nop 1
	v_mul_f32_e32 v22, v51, v51
	v_mul_f32_e32 v23, v53, v53
	v_fmac_f32_e32 v22, v50, v50
	v_fmac_f32_e32 v23, v52, v52
	v_add_f32_e32 v22, v22, v23
	v_mul_f32_e32 v23, v63, v63
	v_mul_f32_e32 v24, v65, v65
	v_fmac_f32_e32 v23, v62, v62
	v_fmac_f32_e32 v24, v64, v64
	v_add_f32_e32 v23, v23, v24
	v_add_f32_e32 v22, v22, v23
	v_add_f32_e32 v26, v30, v22
	ds_swizzle_b32 v27, v26 offset:swizzle(SWAP,16)
	v_cvt_pk_bf16_f32 v22, v50, v51
	v_cvt_pk_bf16_f32 v23, v52, v53
	v_cvt_pk_bf16_f32 v24, v62, v63
	v_cvt_pk_bf16_f32 v25, v64, v65
	flat_store_dwordx4 v[4:5], v[22:25] offset:256
	s_waitcnt lgkmcnt(0)
	v_add_f32_e32 v4, v26, v27
	v_mov_b32_e32 v5, v4
	s_nop 1
	v_permlane32_swap_b32_e32 v4, v5
	v_add_f32_e32 v157, v4, v5
	v_add_u32_e32 v2, 0xb0, v142
	v_ashrrev_i32_e32 v3, 31, v2
	v_lshlrev_b64 v[4:5], 11, v[2:3]
	v_lshl_add_u64 v[4:5], s[2:3], 0, v[4:5]
	v_lshl_add_u64 v[22:23], v[140:141], 1, v[4:5]
	v_mul_f32_e32 v4, v7, v7
	v_mul_f32_e32 v5, v9, v9
	v_fmac_f32_e32 v4, v6, v6
	v_fmac_f32_e32 v5, v8, v8
	v_add_f32_e32 v4, v4, v5
	v_mul_f32_e32 v5, v11, v11
	v_mul_f32_e32 v24, v13, v13
	v_fmac_f32_e32 v5, v10, v10
	v_fmac_f32_e32 v24, v12, v12
	v_add_f32_e32 v5, v5, v24
	v_add_f32_e32 v24, v4, v5
	v_cvt_pk_bf16_f32 v4, v6, v7
	v_cvt_pk_bf16_f32 v5, v8, v9
	v_cvt_pk_bf16_f32 v6, v10, v11
	v_cvt_pk_bf16_f32 v7, v12, v13
	flat_store_dwordx4 v[22:23], v[4:7]
	s_nop 1
	v_mul_f32_e32 v4, v15, v15
	v_mul_f32_e32 v5, v17, v17
	v_fmac_f32_e32 v4, v14, v14
	v_fmac_f32_e32 v5, v16, v16
	v_add_f32_e32 v4, v4, v5
	v_mul_f32_e32 v5, v19, v19
	v_mul_f32_e32 v6, v21, v21
	v_fmac_f32_e32 v5, v18, v18
	v_fmac_f32_e32 v6, v20, v20
	v_add_f32_e32 v5, v5, v6
	v_add_f32_e32 v4, v4, v5
	v_add_f32_e32 v8, v24, v4
	ds_swizzle_b32 v9, v8 offset:swizzle(SWAP,16)
	v_cvt_pk_bf16_f32 v4, v14, v15
	v_cvt_pk_bf16_f32 v5, v16, v17
	v_cvt_pk_bf16_f32 v6, v18, v19
	v_cvt_pk_bf16_f32 v7, v20, v21
	flat_store_dwordx4 v[22:23], v[4:7] offset:256
	s_waitcnt lgkmcnt(0)
	s_nop 0
	v_add_f32_e32 v4, v8, v9
	v_mov_b32_e32 v5, v4
	s_nop 1
	v_permlane32_swap_b32_e32 v4, v5
	v_add_f32_e32 v158, v4, v5
	v_bfe_u32 v160, v193, 4, 2
	v_and_b32_e32 v161, 1, v160
	v_lshl_add_u32 v162, v161, 4, v142
	v_lshlrev_b32_e32 v162, 6, v162
	s_lshl_b32 s0, s4, 4
	s_lshl_b32 s24, s51, 2
	s_or_b32 s0, s0, s24
	v_add_u32_e32 v162, s0, v162
	s_mov_b32 vcc_lo, 0xffff0000
	s_mov_b32 vcc_hi, 0xffff0000
	v_cndmask_b32_e32 v151, v151, v152, vcc
	v_cndmask_b32_e32 v153, v153, v154, vcc
	v_cndmask_b32_e32 v155, v155, v156, vcc
	v_cndmask_b32_e32 v157, v157, v158, vcc
	s_mov_b64 exec, 0xffffffff
	v_add_u32_e32 v163, 0x0, v162
	global_store_dword v163, v151, s[8:9]
	v_add_u32_e32 v163, 0x800, v162
	global_store_dword v163, v153, s[8:9]
	v_add_u32_e32 v163, 0x2000, v162
	global_store_dword v163, v155, s[8:9]
	v_add_u32_e32 v163, 0x2800, v162
	global_store_dword v163, v157, s[8:9]
	s_mov_b64 exec, -1
	s_andn2_b64 vcc, exec, s[38:39]
	s_mov_b64 s[24:25], -1
	s_cbranch_vccnz .LBB0_1011
	v_mov_b32_e32 v3, v193
	s_lshl_b32 s0, s14, 8
	s_add_i32 s0, s0, s55
	v_and_or_b32 v2, v3, 15, s0
	s_lshl_b32 s0, s12, 8
	v_lshrrev_b32_e32 v3, 1, v3
	v_and_or_b32 v3, v3, 24, s0
	v_or_b32_e32 v4, s71, v3
	v_ashrrev_i32_e32 v3, 31, v2
	v_ashrrev_i32_e32 v5, 31, v4
	v_lshlrev_b64 v[6:7], 11, v[2:3]
	v_lshl_add_u64 v[6:7], s[2:3], 0, v[6:7]
	v_lshlrev_b64 v[4:5], 1, v[4:5]
	v_lshl_add_u64 v[10:11], v[6:7], 0, v[4:5]
	v_or_b32_e32 v6, 16, v2
	v_ashrrev_i32_e32 v7, 31, v6
	v_lshlrev_b64 v[6:7], 11, v[6:7]
	v_lshl_add_u64 v[6:7], s[2:3], 0, v[6:7]
	v_lshl_add_u64 v[6:7], v[6:7], 0, v[4:5]
	flat_load_dwordx4 v[62:65], v[10:11]
	flat_load_dwordx4 v[54:57], v[10:11] offset:256
	flat_load_dwordx4 v[58:61], v[6:7]
	flat_load_dwordx4 v[46:49], v[6:7] offset:256
	v_or_b32_e32 v6, 32, v2
	v_or_b32_e32 v2, 48, v2
	v_ashrrev_i32_e32 v7, 31, v6
	v_ashrrev_i32_e32 v3, 31, v2
	v_lshlrev_b64 v[6:7], 11, v[6:7]
	v_lshlrev_b64 v[2:3], 11, v[2:3]
	v_lshl_add_u64 v[6:7], s[2:3], 0, v[6:7]
	v_lshl_add_u64 v[2:3], s[2:3], 0, v[2:3]
	s_mov_b32 s0, 0x40000
	v_lshl_add_u64 v[6:7], v[6:7], 0, v[4:5]
	v_lshl_add_u64 v[2:3], v[2:3], 0, v[4:5]
	v_add_co_u32_e32 v4, vcc, s0, v10
	s_mov_b32 s0, 0x48000
	s_nop 0
	v_addc_co_u32_e32 v5, vcc, 0, v11, vcc
	s_mov_b64 s[24:25], 0x40000
	v_add_co_u32_e32 v8, vcc, s0, v10
	flat_load_dwordx4 v[50:53], v[6:7]
	flat_load_dwordx4 v[34:37], v[6:7] offset:256
	flat_load_dwordx4 v[38:41], v[2:3]
	flat_load_dwordx4 v[22:25], v[2:3] offset:256
	v_lshl_add_u64 v[2:3], v[10:11], 0, s[24:25]
	s_mov_b64 s[24:25], 0x48000
	v_addc_co_u32_e32 v9, vcc, 0, v11, vcc
	flat_load_dwordx4 v[30:33], v[4:5]
	s_nop 0
	flat_load_dwordx4 v[2:5], v[2:3] offset:256
	v_lshl_add_u64 v[6:7], v[10:11], 0, s[24:25]
	flat_load_dwordx4 v[26:29], v[8:9]
	flat_load_dwordx4 v[14:17], v[6:7] offset:256
	s_mov_b64 s[24:25], 0x50000
	v_add_co_u32_e32 v8, vcc, 0x50000, v10
	v_lshl_add_u64 v[6:7], v[10:11], 0, s[24:25]
	s_nop 0
	v_addc_co_u32_e32 v9, vcc, 0, v11, vcc
	s_mov_b64 s[24:25], 0x58000
	v_lshl_add_u64 v[18:19], v[10:11], 0, s[24:25]
	v_add_co_u32_e32 v10, vcc, 0x58000, v10
	flat_load_dwordx4 v[42:45], v[8:9]
	s_nop 0
	flat_load_dwordx4 v[6:9], v[6:7] offset:256
	v_addc_co_u32_e32 v11, vcc, 0, v11, vcc
	flat_load_dwordx4 v[10:13], v[10:11]
	s_nop 0
	flat_load_dwordx4 v[18:21], v[18:19] offset:256
	s_andn2_b64 vcc, exec, s[6:7]
	s_cbranch_vccnz .LBB0_1010
	s_barrier
	s_branch .LBB0_1010

.LBB0_1312:
	s_lshl_b32 s0, s77, 8
	v_mov_b32_e32 v140, v193
	s_add_i32 s0, s0, s44
	v_mul_f32_e32 v148, v115, v115
	v_bfe_u32 v143, v140, 4, 2
	v_and_or_b32 v142, v140, 15, s0
	s_lshl_b32 s0, s4, 8
	v_lshl_or_b32 v140, v143, 3, s0
	v_cmp_eq_u32_e32 vcc, 0, v143
	v_ashrrev_i32_e32 v143, 31, v142
	v_or_b32_e32 v140, s45, v140
	v_lshlrev_b64 v[146:147], 11, v[142:143]
	v_ashrrev_i32_e32 v141, 31, v140
	v_lshl_add_u64 v[146:147], s[2:3], 0, v[146:147]
	v_mul_f32_e32 v149, v117, v117
	v_lshl_add_u64 v[146:147], v[140:141], 1, v[146:147]
	v_fmac_f32_e32 v148, v114, v114
	v_fmac_f32_e32 v149, v116, v116
	v_cvt_pk_bf16_f32 v114, v114, v115
	v_cvt_pk_bf16_f32 v115, v116, v117
	v_cvt_pk_bf16_f32 v116, v118, v119
	v_cvt_pk_bf16_f32 v117, v120, v121
	flat_store_dwordx4 v[146:147], v[114:117]
	v_add_f32_e32 v148, v148, v149
	v_mul_f32_e32 v149, v119, v119
	v_mul_f32_e32 v114, v123, v123
	v_mul_f32_e32 v115, v125, v125
	v_fmac_f32_e32 v114, v122, v122
	v_fmac_f32_e32 v115, v124, v124
	v_mul_f32_e32 v150, v121, v121
	v_add_f32_e32 v114, v114, v115
	v_mul_f32_e32 v115, v127, v127
	v_mul_f32_e32 v116, v129, v129
	v_fmac_f32_e32 v149, v118, v118
	v_fmac_f32_e32 v150, v120, v120
	v_fmac_f32_e32 v115, v126, v126
	v_fmac_f32_e32 v116, v128, v128
	v_add_f32_e32 v149, v149, v150
	v_add_f32_e32 v115, v115, v116
	v_add_f32_e32 v148, v148, v149
	v_add_f32_e32 v114, v114, v115
	v_add_f32_e32 v118, v148, v114
	ds_swizzle_b32 v119, v118 offset:swizzle(SWAP,16)
	v_cvt_pk_bf16_f32 v114, v122, v123
	v_cvt_pk_bf16_f32 v115, v124, v125
	v_cvt_pk_bf16_f32 v116, v126, v127
	v_cvt_pk_bf16_f32 v117, v128, v129
	flat_store_dwordx4 v[146:147], v[114:117] offset:256
	s_lshl_b32 s16, s4, 2
	s_ashr_i32 s17, s16, 31
	s_waitcnt lgkmcnt(0)
	v_add_f32_e32 v114, v118, v119
	v_mov_b32_e32 v115, v114
	s_nop 1
	v_permlane32_swap_b32_e32 v114, v115
	v_add_f32_e32 v151, v114, v115
	v_or_b32_e32 v114, 16, v142
	v_ashrrev_i32_e32 v115, 31, v114
	v_lshlrev_b64 v[116:117], 11, v[114:115]
	v_lshl_add_u64 v[116:117], s[2:3], 0, v[116:117]
	v_mul_f32_e32 v118, v99, v99
	v_mul_f32_e32 v119, v101, v101
	v_lshl_add_u64 v[116:117], v[140:141], 1, v[116:117]
	v_fmac_f32_e32 v118, v98, v98
	v_fmac_f32_e32 v119, v100, v100
	v_cvt_pk_bf16_f32 v98, v98, v99
	v_cvt_pk_bf16_f32 v99, v100, v101
	v_cvt_pk_bf16_f32 v100, v102, v103
	v_cvt_pk_bf16_f32 v101, v104, v105
	flat_store_dwordx4 v[116:117], v[98:101]
	v_add_f32_e32 v118, v118, v119
	v_mul_f32_e32 v119, v103, v103
	v_mul_f32_e32 v98, v107, v107
	v_mul_f32_e32 v99, v109, v109
	v_fmac_f32_e32 v98, v106, v106
	v_fmac_f32_e32 v99, v108, v108
	v_mul_f32_e32 v120, v105, v105
	v_add_f32_e32 v98, v98, v99
	v_mul_f32_e32 v99, v111, v111
	v_mul_f32_e32 v100, v113, v113
	v_fmac_f32_e32 v119, v102, v102
	v_fmac_f32_e32 v120, v104, v104
	v_fmac_f32_e32 v99, v110, v110
	v_fmac_f32_e32 v100, v112, v112
	v_add_f32_e32 v119, v119, v120
	v_add_f32_e32 v99, v99, v100
	v_add_f32_e32 v118, v118, v119
	v_add_f32_e32 v98, v98, v99
	v_add_f32_e32 v102, v118, v98
	ds_swizzle_b32 v103, v102 offset:swizzle(SWAP,16)
	v_cvt_pk_bf16_f32 v98, v106, v107
	v_cvt_pk_bf16_f32 v99, v108, v109
	v_cvt_pk_bf16_f32 v100, v110, v111
	v_cvt_pk_bf16_f32 v101, v112, v113
	flat_store_dwordx4 v[116:117], v[98:101] offset:256
	s_waitcnt lgkmcnt(0)
	s_nop 0
	v_add_f32_e32 v98, v102, v103
	v_mov_b32_e32 v99, v98
	s_nop 1
	v_permlane32_swap_b32_e32 v98, v99
	v_add_f32_e32 v152, v98, v99
	v_or_b32_e32 v98, 32, v142
	v_ashrrev_i32_e32 v99, 31, v98
	v_lshlrev_b64 v[100:101], 11, v[98:99]
	v_lshl_add_u64 v[100:101], s[2:3], 0, v[100:101]
	v_mul_f32_e32 v102, v71, v71
	v_mul_f32_e32 v103, v73, v73
	v_lshl_add_u64 v[100:101], v[140:141], 1, v[100:101]
	v_fmac_f32_e32 v102, v70, v70
	v_fmac_f32_e32 v103, v72, v72
	v_cvt_pk_bf16_f32 v70, v70, v71
	v_cvt_pk_bf16_f32 v71, v72, v73
	v_cvt_pk_bf16_f32 v72, v78, v79
	v_cvt_pk_bf16_f32 v73, v80, v81
	flat_store_dwordx4 v[100:101], v[70:73]
	v_add_f32_e32 v102, v102, v103
	v_mul_f32_e32 v103, v79, v79
	v_mul_f32_e32 v70, v87, v87
	v_mul_f32_e32 v71, v89, v89
	v_fmac_f32_e32 v70, v86, v86
	v_fmac_f32_e32 v71, v88, v88
	v_mul_f32_e32 v104, v81, v81
	v_add_f32_e32 v70, v70, v71
	v_mul_f32_e32 v71, v95, v95
	v_mul_f32_e32 v72, v97, v97
	v_fmac_f32_e32 v103, v78, v78
	v_fmac_f32_e32 v104, v80, v80
	v_fmac_f32_e32 v71, v94, v94
	v_fmac_f32_e32 v72, v96, v96
	v_add_f32_e32 v103, v103, v104
	v_add_f32_e32 v71, v71, v72
	v_add_f32_e32 v102, v102, v103
	v_add_f32_e32 v70, v70, v71
	v_add_f32_e32 v78, v102, v70
	ds_swizzle_b32 v79, v78 offset:swizzle(SWAP,16)
	v_cvt_pk_bf16_f32 v70, v86, v87
	v_cvt_pk_bf16_f32 v71, v88, v89
	v_cvt_pk_bf16_f32 v72, v94, v95
	v_cvt_pk_bf16_f32 v73, v96, v97
	flat_store_dwordx4 v[100:101], v[70:73] offset:256
	s_waitcnt lgkmcnt(0)
	s_nop 0
	v_add_f32_e32 v70, v78, v79
	v_mov_b32_e32 v71, v70
	s_nop 1
	v_permlane32_swap_b32_e32 v70, v71
	v_add_f32_e32 v153, v70, v71
	v_or_b32_e32 v70, 48, v142
	v_ashrrev_i32_e32 v71, 31, v70
	v_lshlrev_b64 v[72:73], 11, v[70:71]
	v_lshl_add_u64 v[72:73], s[2:3], 0, v[72:73]
	v_mul_f32_e32 v78, v35, v35
	v_mul_f32_e32 v79, v37, v37
	v_lshl_add_u64 v[72:73], v[140:141], 1, v[72:73]
	v_fmac_f32_e32 v78, v34, v34
	v_fmac_f32_e32 v79, v36, v36
	v_cvt_pk_bf16_f32 v34, v34, v35
	v_cvt_pk_bf16_f32 v35, v36, v37
	v_cvt_pk_bf16_f32 v36, v46, v47
	v_cvt_pk_bf16_f32 v37, v48, v49
	flat_store_dwordx4 v[72:73], v[34:37]
	v_add_f32_e32 v78, v78, v79
	v_mul_f32_e32 v79, v47, v47
	v_mul_f32_e32 v34, v59, v59
	v_mul_f32_e32 v35, v61, v61
	v_fmac_f32_e32 v34, v58, v58
	v_fmac_f32_e32 v35, v60, v60
	v_mul_f32_e32 v80, v49, v49
	v_add_f32_e32 v34, v34, v35
	v_mul_f32_e32 v35, v67, v67
	v_mul_f32_e32 v36, v69, v69
	v_fmac_f32_e32 v79, v46, v46
	v_fmac_f32_e32 v80, v48, v48
	v_fmac_f32_e32 v35, v66, v66
	v_fmac_f32_e32 v36, v68, v68
	v_add_f32_e32 v79, v79, v80
	v_add_f32_e32 v35, v35, v36
	v_add_f32_e32 v78, v78, v79
	v_add_f32_e32 v34, v34, v35
	v_add_f32_e32 v46, v78, v34
	ds_swizzle_b32 v47, v46 offset:swizzle(SWAP,16)
	v_cvt_pk_bf16_f32 v34, v58, v59
	v_cvt_pk_bf16_f32 v35, v60, v61
	v_cvt_pk_bf16_f32 v36, v66, v67
	v_cvt_pk_bf16_f32 v37, v68, v69
	flat_store_dwordx4 v[72:73], v[34:37] offset:256
	s_waitcnt lgkmcnt(0)
	s_nop 0
	v_add_f32_e32 v34, v46, v47
	v_mov_b32_e32 v35, v34
	s_nop 1
	v_permlane32_swap_b32_e32 v34, v35
	v_add_f32_e32 v154, v34, v35
	v_add_u32_e32 v34, 0x80, v142
	v_ashrrev_i32_e32 v35, 31, v34
	v_lshlrev_b64 v[36:37], 11, v[34:35]
	v_lshl_add_u64 v[36:37], s[2:3], 0, v[36:37]
	v_mul_f32_e32 v46, v23, v23
	v_mul_f32_e32 v47, v25, v25
	v_lshl_add_u64 v[36:37], v[140:141], 1, v[36:37]
	v_fmac_f32_e32 v46, v22, v22
	v_fmac_f32_e32 v47, v24, v24
	v_cvt_pk_bf16_f32 v22, v22, v23
	v_cvt_pk_bf16_f32 v23, v24, v25
	v_cvt_pk_bf16_f32 v24, v30, v31
	v_cvt_pk_bf16_f32 v25, v32, v33
	flat_store_dwordx4 v[36:37], v[22:25]
	v_add_f32_e32 v46, v46, v47
	v_mul_f32_e32 v47, v31, v31
	v_mul_f32_e32 v22, v39, v39
	v_mul_f32_e32 v23, v41, v41
	v_fmac_f32_e32 v22, v38, v38
	v_fmac_f32_e32 v23, v40, v40
	v_mul_f32_e32 v48, v33, v33
	v_add_f32_e32 v22, v22, v23
	v_mul_f32_e32 v23, v55, v55
	v_mul_f32_e32 v24, v57, v57
	v_fmac_f32_e32 v47, v30, v30
	v_fmac_f32_e32 v48, v32, v32
	v_fmac_f32_e32 v23, v54, v54
	v_fmac_f32_e32 v24, v56, v56
	v_add_f32_e32 v47, v47, v48
	v_add_f32_e32 v23, v23, v24
	v_add_f32_e32 v46, v46, v47
	v_add_f32_e32 v22, v22, v23
	v_add_f32_e32 v30, v46, v22
	ds_swizzle_b32 v31, v30 offset:swizzle(SWAP,16)
	v_cvt_pk_bf16_f32 v22, v38, v39
	v_cvt_pk_bf16_f32 v23, v40, v41
	v_cvt_pk_bf16_f32 v24, v54, v55
	v_cvt_pk_bf16_f32 v25, v56, v57
	flat_store_dwordx4 v[36:37], v[22:25] offset:256
	s_waitcnt lgkmcnt(0)
	s_nop 0
	v_add_f32_e32 v22, v30, v31
	v_mov_b32_e32 v23, v22
	s_nop 1
	v_permlane32_swap_b32_e32 v22, v23
	v_add_f32_e32 v155, v22, v23
	v_add_u32_e32 v22, 0x90, v142
	v_ashrrev_i32_e32 v23, 31, v22
	v_lshlrev_b64 v[24:25], 11, v[22:23]
	v_lshl_add_u64 v[24:25], s[2:3], 0, v[24:25]
	v_mul_f32_e32 v30, v3, v3
	v_mul_f32_e32 v31, v5, v5
	v_lshl_add_u64 v[24:25], v[140:141], 1, v[24:25]
	v_fmac_f32_e32 v30, v2, v2
	v_fmac_f32_e32 v31, v4, v4
	v_cvt_pk_bf16_f32 v2, v2, v3
	v_cvt_pk_bf16_f32 v3, v4, v5
	v_cvt_pk_bf16_f32 v4, v74, v75
	v_cvt_pk_bf16_f32 v5, v76, v77
	flat_store_dwordx4 v[24:25], v[2:5]
	v_add_f32_e32 v30, v30, v31
	v_mul_f32_e32 v31, v75, v75
	v_mul_f32_e32 v2, v83, v83
	v_mul_f32_e32 v3, v85, v85
	v_fmac_f32_e32 v2, v82, v82
	v_fmac_f32_e32 v3, v84, v84
	v_mul_f32_e32 v32, v77, v77
	v_add_f32_e32 v2, v2, v3
	v_mul_f32_e32 v3, v91, v91
	v_mul_f32_e32 v4, v93, v93
	v_fmac_f32_e32 v31, v74, v74
	v_fmac_f32_e32 v32, v76, v76
	v_fmac_f32_e32 v3, v90, v90
	v_fmac_f32_e32 v4, v92, v92
	v_add_f32_e32 v31, v31, v32
	v_add_f32_e32 v3, v3, v4
	v_add_f32_e32 v30, v30, v31
	v_add_f32_e32 v2, v2, v3
	v_add_f32_e32 v30, v30, v2
	ds_swizzle_b32 v31, v30 offset:swizzle(SWAP,16)
	v_cvt_pk_bf16_f32 v2, v82, v83
	v_cvt_pk_bf16_f32 v3, v84, v85
	v_cvt_pk_bf16_f32 v4, v90, v91
	v_cvt_pk_bf16_f32 v5, v92, v93
	flat_store_dwordx4 v[24:25], v[2:5] offset:256
	s_waitcnt lgkmcnt(0)
	s_nop 0
	v_add_f32_e32 v2, v30, v31
	v_mov_b32_e32 v3, v2
	s_nop 1
	v_permlane32_swap_b32_e32 v2, v3
	v_add_f32_e32 v156, v2, v3
	v_mul_f32_e32 v22, v27, v27
	v_mul_f32_e32 v23, v29, v29
	v_add_u32_e32 v2, 0xa0, v142
	v_fmac_f32_e32 v22, v26, v26
	v_fmac_f32_e32 v23, v28, v28
	v_ashrrev_i32_e32 v3, 31, v2
	v_add_f32_e32 v22, v22, v23
	v_mul_f32_e32 v23, v43, v43
	v_mul_f32_e32 v24, v45, v45
	v_lshlrev_b64 v[4:5], 11, v[2:3]
	v_fmac_f32_e32 v23, v42, v42
	v_fmac_f32_e32 v24, v44, v44
	v_lshl_add_u64 v[4:5], s[2:3], 0, v[4:5]
	v_add_f32_e32 v23, v23, v24
	v_lshl_add_u64 v[4:5], v[140:141], 1, v[4:5]
	v_add_f32_e32 v30, v22, v23
	v_cvt_pk_bf16_f32 v22, v26, v27
	v_cvt_pk_bf16_f32 v23, v28, v29
	v_cvt_pk_bf16_f32 v24, v42, v43
	v_cvt_pk_bf16_f32 v25, v44, v45
	flat_store_dwordx4 v[4:5], v[22:25]
	s_nop 1
	v_mul_f32_e32 v22, v51, v51
	v_mul_f32_e32 v23, v53, v53
	v_fmac_f32_e32 v22, v50, v50
	v_fmac_f32_e32 v23, v52, v52
	v_add_f32_e32 v22, v22, v23
	v_mul_f32_e32 v23, v63, v63
	v_mul_f32_e32 v24, v65, v65
	v_fmac_f32_e32 v23, v62, v62
	v_fmac_f32_e32 v24, v64, v64
	v_add_f32_e32 v23, v23, v24
	v_add_f32_e32 v22, v22, v23
	v_add_f32_e32 v26, v30, v22
	ds_swizzle_b32 v27, v26 offset:swizzle(SWAP,16)
	v_cvt_pk_bf16_f32 v22, v50, v51
	v_cvt_pk_bf16_f32 v23, v52, v53
	v_cvt_pk_bf16_f32 v24, v62, v63
	v_cvt_pk_bf16_f32 v25, v64, v65
	flat_store_dwordx4 v[4:5], v[22:25] offset:256
	s_waitcnt lgkmcnt(0)
	v_add_f32_e32 v4, v26, v27
	v_mov_b32_e32 v5, v4
	s_nop 1
	v_permlane32_swap_b32_e32 v4, v5
	v_add_f32_e32 v157, v4, v5
	v_add_u32_e32 v2, 0xb0, v142
	v_ashrrev_i32_e32 v3, 31, v2
	v_lshlrev_b64 v[4:5], 11, v[2:3]
	v_lshl_add_u64 v[4:5], s[2:3], 0, v[4:5]
	v_lshl_add_u64 v[22:23], v[140:141], 1, v[4:5]
	v_mul_f32_e32 v4, v7, v7
	v_mul_f32_e32 v5, v9, v9
	v_fmac_f32_e32 v4, v6, v6
	v_fmac_f32_e32 v5, v8, v8
	v_add_f32_e32 v4, v4, v5
	v_mul_f32_e32 v5, v11, v11
	v_mul_f32_e32 v24, v13, v13
	v_fmac_f32_e32 v5, v10, v10
	v_fmac_f32_e32 v24, v12, v12
	v_add_f32_e32 v5, v5, v24
	v_add_f32_e32 v24, v4, v5
	v_cvt_pk_bf16_f32 v4, v6, v7
	v_cvt_pk_bf16_f32 v5, v8, v9
	v_cvt_pk_bf16_f32 v6, v10, v11
	v_cvt_pk_bf16_f32 v7, v12, v13
	flat_store_dwordx4 v[22:23], v[4:7]
	s_nop 1
	v_mul_f32_e32 v4, v15, v15
	v_mul_f32_e32 v5, v17, v17
	v_fmac_f32_e32 v4, v14, v14
	v_fmac_f32_e32 v5, v16, v16
	v_add_f32_e32 v4, v4, v5
	v_mul_f32_e32 v5, v19, v19
	v_mul_f32_e32 v6, v21, v21
	v_fmac_f32_e32 v5, v18, v18
	v_fmac_f32_e32 v6, v20, v20
	v_add_f32_e32 v5, v5, v6
	v_add_f32_e32 v4, v4, v5
	v_add_f32_e32 v8, v24, v4
	ds_swizzle_b32 v9, v8 offset:swizzle(SWAP,16)
	v_cvt_pk_bf16_f32 v4, v14, v15
	v_cvt_pk_bf16_f32 v5, v16, v17
	v_cvt_pk_bf16_f32 v6, v18, v19
	v_cvt_pk_bf16_f32 v7, v20, v21
	flat_store_dwordx4 v[22:23], v[4:7] offset:256
	s_waitcnt lgkmcnt(0)
	s_nop 0
	v_add_f32_e32 v4, v8, v9
	v_mov_b32_e32 v5, v4
	s_nop 1
	v_permlane32_swap_b32_e32 v4, v5
	v_add_f32_e32 v158, v4, v5
	v_bfe_u32 v160, v193, 4, 2
	v_and_b32_e32 v161, 1, v160
	v_lshl_add_u32 v162, v161, 4, v142
	v_lshlrev_b32_e32 v162, 6, v162
	s_lshl_b32 s0, s4, 4
	s_lshl_b32 s16, s42, 2
	s_or_b32 s0, s0, s16
	v_add_u32_e32 v162, s0, v162
	s_mov_b32 vcc_lo, 0xffff0000
	s_mov_b32 vcc_hi, 0xffff0000
	v_cndmask_b32_e32 v151, v151, v152, vcc
	v_cndmask_b32_e32 v153, v153, v154, vcc
	v_cndmask_b32_e32 v155, v155, v156, vcc
	v_cndmask_b32_e32 v157, v157, v158, vcc
	s_mov_b64 exec, 0xffffffff
	v_add_u32_e32 v163, 0x0, v162
	global_store_dword v163, v151, s[8:9]
	v_add_u32_e32 v163, 0x800, v162
	global_store_dword v163, v153, s[8:9]
	v_add_u32_e32 v163, 0x2000, v162
	global_store_dword v163, v155, s[8:9]
	v_add_u32_e32 v163, 0x2800, v162
	global_store_dword v163, v157, s[8:9]
	s_mov_b64 exec, -1
	s_and_b64 vcc, exec, s[36:37]
	s_mov_b64 s[16:17], -1
	s_cbranch_vccnz .LBB0_1297
	v_mov_b32_e32 v3, v193
	s_lshl_b32 s0, s76, 8
	s_add_i32 s0, s0, s44
	v_and_or_b32 v2, v3, 15, s0
	s_lshl_b32 s0, s75, 8
	v_lshrrev_b32_e32 v3, 1, v3
	v_and_or_b32 v3, v3, 24, s0
	v_or_b32_e32 v4, s45, v3
	v_ashrrev_i32_e32 v3, 31, v2
	v_ashrrev_i32_e32 v5, 31, v4
	v_lshlrev_b64 v[6:7], 11, v[2:3]
	v_lshl_add_u64 v[6:7], s[2:3], 0, v[6:7]
	v_lshlrev_b64 v[4:5], 1, v[4:5]
	v_lshl_add_u64 v[10:11], v[6:7], 0, v[4:5]
	v_or_b32_e32 v6, 16, v2
	v_ashrrev_i32_e32 v7, 31, v6
	v_lshlrev_b64 v[6:7], 11, v[6:7]
	v_lshl_add_u64 v[6:7], s[2:3], 0, v[6:7]
	v_lshl_add_u64 v[6:7], v[6:7], 0, v[4:5]
	flat_load_dwordx4 v[62:65], v[10:11]
	flat_load_dwordx4 v[54:57], v[10:11] offset:256
	flat_load_dwordx4 v[58:61], v[6:7]
	flat_load_dwordx4 v[46:49], v[6:7] offset:256
	v_or_b32_e32 v6, 32, v2
	v_or_b32_e32 v2, 48, v2
	v_ashrrev_i32_e32 v7, 31, v6
	v_ashrrev_i32_e32 v3, 31, v2
	v_lshlrev_b64 v[6:7], 11, v[6:7]
	v_lshlrev_b64 v[2:3], 11, v[2:3]
	v_lshl_add_u64 v[6:7], s[2:3], 0, v[6:7]
	v_lshl_add_u64 v[2:3], s[2:3], 0, v[2:3]
	s_mov_b32 s0, 0x40000
	v_lshl_add_u64 v[6:7], v[6:7], 0, v[4:5]
	v_lshl_add_u64 v[2:3], v[2:3], 0, v[4:5]
	v_add_co_u32_e32 v4, vcc, s0, v10
	s_mov_b32 s0, 0x48000
	s_nop 0
	v_addc_co_u32_e32 v5, vcc, 0, v11, vcc
	s_mov_b64 s[16:17], 0x40000
	v_add_co_u32_e32 v8, vcc, s0, v10
	flat_load_dwordx4 v[50:53], v[6:7]
	flat_load_dwordx4 v[34:37], v[6:7] offset:256
	flat_load_dwordx4 v[38:41], v[2:3]
	flat_load_dwordx4 v[22:25], v[2:3] offset:256
	v_lshl_add_u64 v[2:3], v[10:11], 0, s[16:17]
	s_mov_b64 s[16:17], 0x48000
	v_addc_co_u32_e32 v9, vcc, 0, v11, vcc
	flat_load_dwordx4 v[30:33], v[4:5]
	s_nop 0
	flat_load_dwordx4 v[2:5], v[2:3] offset:256
	v_lshl_add_u64 v[6:7], v[10:11], 0, s[16:17]
	flat_load_dwordx4 v[26:29], v[8:9]
	flat_load_dwordx4 v[14:17], v[6:7] offset:256
	s_mov_b64 s[16:17], 0x50000
	v_add_co_u32_e32 v8, vcc, 0x50000, v10
	v_lshl_add_u64 v[6:7], v[10:11], 0, s[16:17]
	s_nop 0
	v_addc_co_u32_e32 v9, vcc, 0, v11, vcc
	s_mov_b64 s[16:17], 0x58000
	v_lshl_add_u64 v[18:19], v[10:11], 0, s[16:17]
	v_add_co_u32_e32 v10, vcc, 0x58000, v10
	flat_load_dwordx4 v[42:45], v[8:9]
	s_nop 0
	flat_load_dwordx4 v[6:9], v[6:7] offset:256
	v_addc_co_u32_e32 v11, vcc, 0, v11, vcc
	flat_load_dwordx4 v[10:13], v[10:11]
	s_nop 0
	flat_load_dwordx4 v[18:21], v[18:19] offset:256
	s_andn2_b64 vcc, exec, s[6:7]
	s_cbranch_vccnz .LBB0_1296
	s_barrier
	s_branch .LBB0_1296
